# indexer scores: in-register quad transpose so score-scratch stores are 64-byte contiguous per lane quad
# speedup vs baseline: 1.0049x; 1.0049x over previous
; __device__ __forceinline__ void phaseB(const Params& p, LAS unsigned char* lds, int wv) {
;     ...
;                 float* sp = SC + (size_t)(32 * qg + r32) * SEQ + k0 + 8 * hi;
;                 *(f32x4*)(sp) = (f32x4){acc0[0], acc0[1], acc0[2], acc0[3]}; *(f32x4*)(sp + 4) = (f32x4){acc0[4], acc0[5], acc0[6], acc0[7]};
;                 *(f32x4*)(sp + 16) = (f32x4){acc0[8], acc0[9], acc0[10], acc0[11]}; *(f32x4*)(sp + 20) = (f32x4){acc0[12], acc0[13], acc0[14], acc0[15]};
;                 *(f32x4*)(sp + 32) = (f32x4){acc1[0], acc1[1], acc1[2], acc1[3]}; *(f32x4*)(sp + 36) = (f32x4){acc1[4], acc1[5], acc1[6], acc1[7]};
;                 *(f32x4*)(sp + 48) = (f32x4){acc1[8], acc1[9], acc1[10], acc1[11]}; *(f32x4*)(sp + 52) = (f32x4){acc1[12], acc1[13], acc1[14], acc1[15]};
.LBB0_407:
	v_permlane32_swap_b32_e32 v88, v72
	v_permlane32_swap_b32_e32 v89, v73
	v_permlane32_swap_b32_e32 v90, v74
	v_permlane32_swap_b32_e32 v91, v75
	v_permlane32_swap_b32_e32 v80, v64
	v_permlane32_swap_b32_e32 v81, v65
	v_permlane32_swap_b32_e32 v82, v66
	v_permlane32_swap_b32_e32 v83, v67
	v_permlane32_swap_b32_e32 v92, v76
	v_permlane32_swap_b32_e32 v93, v77
	v_permlane32_swap_b32_e32 v94, v78
	v_permlane32_swap_b32_e32 v95, v79
	v_permlane32_swap_b32_e32 v84, v68
	v_permlane32_swap_b32_e32 v85, v69
	v_permlane32_swap_b32_e32 v86, v70
	v_permlane32_swap_b32_e32 v87, v71
	v_mbcnt_lo_u32_b32 v0, -1, 0
	v_mbcnt_hi_u32_b32 v0, -1, v0
	v_and_b32_e32 v1, 3, v0
	v_lshrrev_b32_e32 v2, 5, v0
	v_mul_i32_i24_e32 v1, 0xffffc010, v1
	v_lshl_add_u32 v2, v2, 5, v1
	v_ashrrev_i32_e32 v3, 31, v2
	s_lshl_b32 s2, s4, 6
	s_ashr_i32 s3, s2, 31
	v_lshl_add_u64 v[184:185], s[2:3], 2, v[130:131]
	v_lshl_add_u64 v[184:185], v[184:185], 0, v[2:3]
	s_mov_b64 s[100:101], 0x4000
	v_lshl_add_u64 v[186:187], v[184:185], 0, s[100:101]
	v_lshl_add_u64 v[188:189], v[186:187], 0, s[100:101]
	v_lshl_add_u64 v[190:191], v[188:189], 0, s[100:101]
	s_mov_b32 vcc_lo, 0x55555555
	s_mov_b32 vcc_hi, 0x55555555
	s_nop 1
	v_cndmask_b32_dpp v152, v80, v88, vcc quad_perm:[1,0,3,2] row_mask:0xf bank_mask:0xf
	v_cndmask_b32_dpp v160, v64, v72, vcc quad_perm:[1,0,3,2] row_mask:0xf bank_mask:0xf
	v_cndmask_b32_dpp v153, v81, v89, vcc quad_perm:[1,0,3,2] row_mask:0xf bank_mask:0xf
	v_cndmask_b32_dpp v161, v65, v73, vcc quad_perm:[1,0,3,2] row_mask:0xf bank_mask:0xf
	v_cndmask_b32_dpp v154, v82, v90, vcc quad_perm:[1,0,3,2] row_mask:0xf bank_mask:0xf
	v_cndmask_b32_dpp v162, v66, v74, vcc quad_perm:[1,0,3,2] row_mask:0xf bank_mask:0xf
	v_cndmask_b32_dpp v155, v83, v91, vcc quad_perm:[1,0,3,2] row_mask:0xf bank_mask:0xf
	v_cndmask_b32_dpp v163, v67, v75, vcc quad_perm:[1,0,3,2] row_mask:0xf bank_mask:0xf
	v_cndmask_b32_dpp v168, v84, v92, vcc quad_perm:[1,0,3,2] row_mask:0xf bank_mask:0xf
	v_cndmask_b32_dpp v176, v68, v76, vcc quad_perm:[1,0,3,2] row_mask:0xf bank_mask:0xf
	v_cndmask_b32_dpp v169, v85, v93, vcc quad_perm:[1,0,3,2] row_mask:0xf bank_mask:0xf
	v_cndmask_b32_dpp v177, v69, v77, vcc quad_perm:[1,0,3,2] row_mask:0xf bank_mask:0xf
	v_cndmask_b32_dpp v170, v86, v94, vcc quad_perm:[1,0,3,2] row_mask:0xf bank_mask:0xf
	v_cndmask_b32_dpp v178, v70, v78, vcc quad_perm:[1,0,3,2] row_mask:0xf bank_mask:0xf
	v_cndmask_b32_dpp v171, v87, v95, vcc quad_perm:[1,0,3,2] row_mask:0xf bank_mask:0xf
	v_cndmask_b32_dpp v179, v71, v79, vcc quad_perm:[1,0,3,2] row_mask:0xf bank_mask:0xf
	s_not_b64 vcc, vcc
	s_nop 1
	v_cndmask_b32_dpp v156, v88, v80, vcc quad_perm:[1,0,3,2] row_mask:0xf bank_mask:0xf
	v_cndmask_b32_dpp v164, v72, v64, vcc quad_perm:[1,0,3,2] row_mask:0xf bank_mask:0xf
	v_cndmask_b32_dpp v157, v89, v81, vcc quad_perm:[1,0,3,2] row_mask:0xf bank_mask:0xf
	v_cndmask_b32_dpp v165, v73, v65, vcc quad_perm:[1,0,3,2] row_mask:0xf bank_mask:0xf
	v_cndmask_b32_dpp v158, v90, v82, vcc quad_perm:[1,0,3,2] row_mask:0xf bank_mask:0xf
	v_cndmask_b32_dpp v166, v74, v66, vcc quad_perm:[1,0,3,2] row_mask:0xf bank_mask:0xf
	v_cndmask_b32_dpp v159, v91, v83, vcc quad_perm:[1,0,3,2] row_mask:0xf bank_mask:0xf
	v_cndmask_b32_dpp v167, v75, v67, vcc quad_perm:[1,0,3,2] row_mask:0xf bank_mask:0xf
	v_cndmask_b32_dpp v172, v92, v84, vcc quad_perm:[1,0,3,2] row_mask:0xf bank_mask:0xf
	v_cndmask_b32_dpp v180, v76, v68, vcc quad_perm:[1,0,3,2] row_mask:0xf bank_mask:0xf
	v_cndmask_b32_dpp v173, v93, v85, vcc quad_perm:[1,0,3,2] row_mask:0xf bank_mask:0xf
	v_cndmask_b32_dpp v181, v77, v69, vcc quad_perm:[1,0,3,2] row_mask:0xf bank_mask:0xf
	v_cndmask_b32_dpp v174, v94, v86, vcc quad_perm:[1,0,3,2] row_mask:0xf bank_mask:0xf
; __device__ __forceinline__ void phaseB(const Params& p, LAS unsigned char* lds, int wv) {
;     ...
;                 float* sp = SC + (size_t)(32 * qg + r32) * SEQ + k0 + 8 * hi;
;                 *(f32x4*)(sp) = (f32x4){acc0[0], acc0[1], acc0[2], acc0[3]}; *(f32x4*)(sp + 4) = (f32x4){acc0[4], acc0[5], acc0[6], acc0[7]};
;                 *(f32x4*)(sp + 16) = (f32x4){acc0[8], acc0[9], acc0[10], acc0[11]}; *(f32x4*)(sp + 20) = (f32x4){acc0[12], acc0[13], acc0[14], acc0[15]};
;                 *(f32x4*)(sp + 32) = (f32x4){acc1[0], acc1[1], acc1[2], acc1[3]}; *(f32x4*)(sp + 36) = (f32x4){acc1[4], acc1[5], acc1[6], acc1[7]};
;                 *(f32x4*)(sp + 48) = (f32x4){acc1[8], acc1[9], acc1[10], acc1[11]}; *(f32x4*)(sp + 52) = (f32x4){acc1[12], acc1[13], acc1[14], acc1[15]};
	v_cndmask_b32_dpp v182, v78, v70, vcc quad_perm:[1,0,3,2] row_mask:0xf bank_mask:0xf
	v_cndmask_b32_dpp v175, v95, v87, vcc quad_perm:[1,0,3,2] row_mask:0xf bank_mask:0xf
	v_cndmask_b32_dpp v183, v79, v71, vcc quad_perm:[1,0,3,2] row_mask:0xf bank_mask:0xf
	s_mov_b32 vcc_lo, 0x33333333
	s_mov_b32 vcc_hi, 0x33333333
	s_nop 1
	v_cndmask_b32_dpp v88, v160, v152, vcc quad_perm:[2,3,0,1] row_mask:0xf bank_mask:0xf
	v_cndmask_b32_dpp v80, v164, v156, vcc quad_perm:[2,3,0,1] row_mask:0xf bank_mask:0xf
	v_cndmask_b32_dpp v89, v161, v153, vcc quad_perm:[2,3,0,1] row_mask:0xf bank_mask:0xf
	v_cndmask_b32_dpp v81, v165, v157, vcc quad_perm:[2,3,0,1] row_mask:0xf bank_mask:0xf
	v_cndmask_b32_dpp v90, v162, v154, vcc quad_perm:[2,3,0,1] row_mask:0xf bank_mask:0xf
	v_cndmask_b32_dpp v82, v166, v158, vcc quad_perm:[2,3,0,1] row_mask:0xf bank_mask:0xf
	v_cndmask_b32_dpp v91, v163, v155, vcc quad_perm:[2,3,0,1] row_mask:0xf bank_mask:0xf
	v_cndmask_b32_dpp v83, v167, v159, vcc quad_perm:[2,3,0,1] row_mask:0xf bank_mask:0xf
	v_cndmask_b32_dpp v92, v176, v168, vcc quad_perm:[2,3,0,1] row_mask:0xf bank_mask:0xf
	v_cndmask_b32_dpp v84, v180, v172, vcc quad_perm:[2,3,0,1] row_mask:0xf bank_mask:0xf
	v_cndmask_b32_dpp v93, v177, v169, vcc quad_perm:[2,3,0,1] row_mask:0xf bank_mask:0xf
	v_cndmask_b32_dpp v85, v181, v173, vcc quad_perm:[2,3,0,1] row_mask:0xf bank_mask:0xf
	v_cndmask_b32_dpp v94, v178, v170, vcc quad_perm:[2,3,0,1] row_mask:0xf bank_mask:0xf
	v_cndmask_b32_dpp v86, v182, v174, vcc quad_perm:[2,3,0,1] row_mask:0xf bank_mask:0xf
	v_cndmask_b32_dpp v95, v179, v171, vcc quad_perm:[2,3,0,1] row_mask:0xf bank_mask:0xf
	v_cndmask_b32_dpp v87, v183, v175, vcc quad_perm:[2,3,0,1] row_mask:0xf bank_mask:0xf
	s_not_b64 vcc, vcc
	s_nop 1
	v_cndmask_b32_dpp v72, v152, v160, vcc quad_perm:[2,3,0,1] row_mask:0xf bank_mask:0xf
	v_cndmask_b32_dpp v64, v156, v164, vcc quad_perm:[2,3,0,1] row_mask:0xf bank_mask:0xf
	v_cndmask_b32_dpp v73, v153, v161, vcc quad_perm:[2,3,0,1] row_mask:0xf bank_mask:0xf
	v_cndmask_b32_dpp v65, v157, v165, vcc quad_perm:[2,3,0,1] row_mask:0xf bank_mask:0xf
	v_cndmask_b32_dpp v74, v154, v162, vcc quad_perm:[2,3,0,1] row_mask:0xf bank_mask:0xf
	v_cndmask_b32_dpp v66, v158, v166, vcc quad_perm:[2,3,0,1] row_mask:0xf bank_mask:0xf
	v_cndmask_b32_dpp v75, v155, v163, vcc quad_perm:[2,3,0,1] row_mask:0xf bank_mask:0xf
	v_cndmask_b32_dpp v67, v159, v167, vcc quad_perm:[2,3,0,1] row_mask:0xf bank_mask:0xf
	v_cndmask_b32_dpp v76, v168, v176, vcc quad_perm:[2,3,0,1] row_mask:0xf bank_mask:0xf
	v_cndmask_b32_dpp v68, v172, v180, vcc quad_perm:[2,3,0,1] row_mask:0xf bank_mask:0xf
	v_cndmask_b32_dpp v77, v169, v177, vcc quad_perm:[2,3,0,1] row_mask:0xf bank_mask:0xf
	v_cndmask_b32_dpp v69, v173, v181, vcc quad_perm:[2,3,0,1] row_mask:0xf bank_mask:0xf
	v_cndmask_b32_dpp v78, v170, v178, vcc quad_perm:[2,3,0,1] row_mask:0xf bank_mask:0xf
	v_cndmask_b32_dpp v70, v174, v182, vcc quad_perm:[2,3,0,1] row_mask:0xf bank_mask:0xf
	v_cndmask_b32_dpp v79, v171, v179, vcc quad_perm:[2,3,0,1] row_mask:0xf bank_mask:0xf
	v_cndmask_b32_dpp v71, v175, v183, vcc quad_perm:[2,3,0,1] row_mask:0xf bank_mask:0xf
	s_nop 0
	global_store_dwordx4 v[184:185], v[88:91], off
	global_store_dwordx4 v[184:185], v[92:95], off offset:128
	global_store_dwordx4 v[186:187], v[80:83], off
	global_store_dwordx4 v[186:187], v[84:87], off offset:128
	global_store_dwordx4 v[188:189], v[72:75], off
	global_store_dwordx4 v[188:189], v[76:79], off offset:128
	global_store_dwordx4 v[190:191], v[64:67], off
	global_store_dwordx4 v[190:191], v[68:71], off offset:128
	s_add_i32 s4, s4, 4
	s_cmp_gt_i32 s4, s33
	s_cbranch_scc1 .LBB0_475

; #define LAS __attribute__((address_space(3)))
; __device__ __forceinline__ void phaseB(const Params& p, LAS unsigned char* lds, int wv) {
;     ...
; #pragma unroll 2
;                 for (int hh = 0; hh < 8; ++hh) {
;                     const float wh = wp[hh];
;                     f32x16 s0, s1;
; #pragma unroll
;                     for (int r = 0; r < 16; ++r) { s0[r] = 0.f; s1[r] = 0.f; }
; #pragma unroll
;                     for (int ds = 0; ds < 4; ++ds) { const f16x8 qfr = *(const LAS f16x8*)(qp + hh * 128 + ds * 32);
;                         s0 = __builtin_amdgcn_mfma_f32_32x32x16_f16(kf[0][ds], qfr, s0, 0, 0, 0); s1 = __builtin_amdgcn_mfma_f32_32x32x16_f16(kf[1][ds], qfr, s1, 0, 0, 0); }
; #pragma unroll
;                     for (int r = 0; r < 16; ++r) { acc0[r] += wh * fmaxf(s0[r], 0.f); acc1[r] += wh * fmaxf(s1[r], 0.f); }
;                 }
;                 float* sp = SC + (size_t)(32 * qg + r32) * SEQ + k0 + 8 * hi;
;                 *(f32x4*)(sp) = (f32x4){acc0[0], acc0[1], acc0[2], acc0[3]}; *(f32x4*)(sp + 4) = (f32x4){acc0[4], acc0[5], acc0[6], acc0[7]};
;                 *(f32x4*)(sp + 16) = (f32x4){acc0[8], acc0[9], acc0[10], acc0[11]}; *(f32x4*)(sp + 20) = (f32x4){acc0[12], acc0[13], acc0[14], acc0[15]};
;                 *(f32x4*)(sp + 32) = (f32x4){acc1[0], acc1[1], acc1[2], acc1[3]}; *(f32x4*)(sp + 36) = (f32x4){acc1[4], acc1[5], acc1[6], acc1[7]};
;                 *(f32x4*)(sp + 48) = (f32x4){acc1[8], acc1[9], acc1[10], acc1[11]}; *(f32x4*)(sp + 52) = (f32x4){acc1[12], acc1[13], acc1[14], acc1[15]};
.LBB0_409:
	v_add_u32_e32 v139, s5, v132
	ds_read_b128 v[0:3], v139
	ds_read_b128 v[140:143], v139 offset:32
	ds_read_b128 v[48:51], v139 offset:128
	ds_read_b128 v[144:147], v139 offset:160
	s_addk_i32 s5, 0x100
	s_cmpk_eq_i32 s5, 0x400
	s_waitcnt vmcnt(7) lgkmcnt(3)
	v_mfma_f32_32x32x16_f16 v[16:31], v[96:99], v[0:3], 0
	s_waitcnt vmcnt(3)
	v_mfma_f32_32x32x16_f16 v[0:15], v[112:115], v[0:3], 0
	s_waitcnt lgkmcnt(1)
	v_mfma_f32_32x32x16_f16 v[32:47], v[96:99], v[48:51], 0
	v_mfma_f32_32x32x16_f16 v[48:63], v[112:115], v[48:51], 0
	v_mfma_f32_32x32x16_f16 v[16:31], v[100:103], v[140:143], v[16:31]
	s_waitcnt vmcnt(2)
	v_mfma_f32_32x32x16_f16 v[0:15], v[116:119], v[140:143], v[0:15]
	s_waitcnt lgkmcnt(0)
	v_mfma_f32_32x32x16_f16 v[32:47], v[100:103], v[144:147], v[32:47]
	v_mfma_f32_32x32x16_f16 v[48:63], v[116:119], v[144:147], v[48:63]
	ds_read_b128 v[140:143], v139 offset:64
	ds_read_b128 v[144:147], v139 offset:96
	s_waitcnt lgkmcnt(1)
	v_mfma_f32_32x32x16_f16 v[16:31], v[104:107], v[140:143], v[16:31]
	s_waitcnt vmcnt(1)
	v_mfma_f32_32x32x16_f16 v[0:15], v[120:123], v[140:143], v[0:15]
	ds_read_b128 v[140:143], v139 offset:192
	ds_read_b128 v[148:151], v139 offset:224
	v_add_u32_e32 v139, -4, v138
	v_add_u32_e32 v138, 8, v138
	s_waitcnt lgkmcnt(1)
	v_mfma_f32_32x32x16_f16 v[32:47], v[104:107], v[140:143], v[32:47]
	v_mfma_f32_32x32x16_f16 v[48:63], v[120:123], v[140:143], v[48:63]
	ds_read_b64 v[140:141], v139
	v_mfma_f32_32x32x16_f16 v[16:31], v[108:111], v[144:147], v[16:31]
	s_waitcnt vmcnt(0)
	v_mfma_f32_32x32x16_f16 v[0:15], v[124:127], v[144:147], v[0:15]
	s_nop 9
	v_max_f32_e32 v16, 0, v16
	v_max_f32_e32 v17, 0, v17
	v_max_f32_e32 v18, 0, v18
	v_max_f32_e32 v19, 0, v19
	v_max_f32_e32 v20, 0, v20
	v_max_f32_e32 v21, 0, v21
	v_max_f32_e32 v22, 0, v22
	s_waitcnt lgkmcnt(1)
	v_mfma_f32_32x32x16_f16 v[32:47], v[108:111], v[148:151], v[32:47]
	v_max_f32_e32 v23, 0, v23
	v_max_f32_e32 v24, 0, v24
	v_max_f32_e32 v25, 0, v25
	v_max_f32_e32 v26, 0, v26
	v_max_f32_e32 v27, 0, v27
	v_max_f32_e32 v28, 0, v28
	v_max_f32_e32 v29, 0, v29
	v_mfma_f32_32x32x16_f16 v[48:63], v[124:127], v[148:151], v[48:63]
	v_max_f32_e32 v30, 0, v30
	v_max_f32_e32 v31, 0, v31
	v_max_f32_e32 v0, 0, v0
	v_max_f32_e32 v1, 0, v1
	v_max_f32_e32 v2, 0, v2
	v_max_f32_e32 v3, 0, v3
	v_max_f32_e32 v4, 0, v4
	v_max_f32_e32 v5, 0, v5
	v_max_f32_e32 v6, 0, v6
	v_max_f32_e32 v7, 0, v7
	v_max_f32_e32 v8, 0, v8
	v_max_f32_e32 v9, 0, v9
	v_max_f32_e32 v10, 0, v10
	v_max_f32_e32 v11, 0, v11
	v_max_f32_e32 v12, 0, v12
	v_max_f32_e32 v13, 0, v13
	v_max_f32_e32 v14, 0, v14
	v_max_f32_e32 v15, 0, v15
	v_max_f32_e32 v32, 0, v32
	v_max_f32_e32 v33, 0, v33
	v_max_f32_e32 v34, 0, v34
	v_max_f32_e32 v35, 0, v35
	v_max_f32_e32 v36, 0, v36
	v_max_f32_e32 v37, 0, v37
	v_max_f32_e32 v38, 0, v38
	v_max_f32_e32 v39, 0, v39
	v_max_f32_e32 v40, 0, v40
	v_max_f32_e32 v41, 0, v41
	v_max_f32_e32 v42, 0, v42
	v_max_f32_e32 v43, 0, v43
	v_max_f32_e32 v44, 0, v44
	v_max_f32_e32 v45, 0, v45
	v_max_f32_e32 v46, 0, v46
	v_max_f32_e32 v47, 0, v47
	v_max_f32_e32 v48, 0, v48
	v_max_f32_e32 v49, 0, v49
	v_max_f32_e32 v50, 0, v50
	v_max_f32_e32 v51, 0, v51
	v_max_f32_e32 v52, 0, v52
	v_max_f32_e32 v53, 0, v53
	v_max_f32_e32 v54, 0, v54
	v_max_f32_e32 v55, 0, v55
	v_max_f32_e32 v56, 0, v56
	v_max_f32_e32 v57, 0, v57
	v_max_f32_e32 v58, 0, v58
	v_max_f32_e32 v59, 0, v59
	v_max_f32_e32 v60, 0, v60
	v_max_f32_e32 v61, 0, v61
	v_max_f32_e32 v62, 0, v62
	v_max_f32_e32 v63, 0, v63
	s_waitcnt lgkmcnt(0)
	v_pk_fma_f32 v[88:89], v[140:141], v[16:17], v[88:89] op_sel_hi:[0,1,1]
	v_pk_fma_f32 v[92:93], v[140:141], v[0:1], v[92:93] op_sel_hi:[0,1,1]
	v_pk_fma_f32 v[90:91], v[140:141], v[18:19], v[90:91] op_sel_hi:[0,1,1]
	v_pk_fma_f32 v[94:95], v[140:141], v[2:3], v[94:95] op_sel_hi:[0,1,1]
	v_pk_fma_f32 v[80:81], v[140:141], v[20:21], v[80:81] op_sel_hi:[0,1,1]
	v_pk_fma_f32 v[84:85], v[140:141], v[4:5], v[84:85] op_sel_hi:[0,1,1]
	v_pk_fma_f32 v[82:83], v[140:141], v[22:23], v[82:83] op_sel_hi:[0,1,1]
	v_pk_fma_f32 v[86:87], v[140:141], v[6:7], v[86:87] op_sel_hi:[0,1,1]
	v_pk_fma_f32 v[72:73], v[140:141], v[24:25], v[72:73] op_sel_hi:[0,1,1]
	v_pk_fma_f32 v[76:77], v[140:141], v[8:9], v[76:77] op_sel_hi:[0,1,1]
	v_pk_fma_f32 v[74:75], v[140:141], v[26:27], v[74:75] op_sel_hi:[0,1,1]
	v_pk_fma_f32 v[78:79], v[140:141], v[10:11], v[78:79] op_sel_hi:[0,1,1]
	v_pk_fma_f32 v[64:65], v[140:141], v[28:29], v[64:65] op_sel_hi:[0,1,1]
	v_pk_fma_f32 v[68:69], v[140:141], v[12:13], v[68:69] op_sel_hi:[0,1,1]
	v_pk_fma_f32 v[66:67], v[140:141], v[30:31], v[66:67] op_sel_hi:[0,1,1]
	v_pk_fma_f32 v[70:71], v[140:141], v[14:15], v[70:71] op_sel_hi:[0,1,1]
	v_pk_fma_f32 v[88:89], v[140:141], v[32:33], v[88:89] op_sel:[1,0,0]
	v_pk_fma_f32 v[92:93], v[140:141], v[48:49], v[92:93] op_sel:[1,0,0]
	v_pk_fma_f32 v[90:91], v[140:141], v[34:35], v[90:91] op_sel:[1,0,0]
	v_pk_fma_f32 v[94:95], v[140:141], v[50:51], v[94:95] op_sel:[1,0,0]
	v_pk_fma_f32 v[80:81], v[140:141], v[36:37], v[80:81] op_sel:[1,0,0]
	v_pk_fma_f32 v[84:85], v[140:141], v[52:53], v[84:85] op_sel:[1,0,0]
	v_pk_fma_f32 v[82:83], v[140:141], v[38:39], v[82:83] op_sel:[1,0,0]
	v_pk_fma_f32 v[86:87], v[140:141], v[54:55], v[86:87] op_sel:[1,0,0]
	v_pk_fma_f32 v[72:73], v[140:141], v[40:41], v[72:73] op_sel:[1,0,0]
	v_pk_fma_f32 v[76:77], v[140:141], v[56:57], v[76:77] op_sel:[1,0,0]
	v_pk_fma_f32 v[74:75], v[140:141], v[42:43], v[74:75] op_sel:[1,0,0]
	v_pk_fma_f32 v[78:79], v[140:141], v[58:59], v[78:79] op_sel:[1,0,0]
	v_pk_fma_f32 v[64:65], v[140:141], v[44:45], v[64:65] op_sel:[1,0,0]
	v_pk_fma_f32 v[68:69], v[140:141], v[60:61], v[68:69] op_sel:[1,0,0]
	v_pk_fma_f32 v[66:67], v[140:141], v[46:47], v[66:67] op_sel:[1,0,0]
	v_pk_fma_f32 v[70:71], v[140:141], v[62:63], v[70:71] op_sel:[1,0,0]
	s_cbranch_scc0 .LBB0_409
	s_and_b64 vcc, exec, s[0:1]
	s_cbranch_vccz .LBB0_407
	s_add_i32 s100, s2, 63
	s_cmp_le_i32 s100, s99
	s_cbranch_scc1 .Lb1_fast_hist
	v_or_b32_e32 v0, s2, v135
	s_nop 0
	v_cmp_le_i32_e32 vcc, v0, v134
	s_and_saveexec_b64 s[2:3], vcc
	s_cbranch_execz .LBB0_413
	v_cmp_lt_i32_e32 vcc, -1, v88
	s_nop 1
	v_cndmask_b32_e32 v1, -1, v230, vcc
	v_xor_b32_e32 v1, v1, v88
	v_lshrrev_b32_e32 v1, 24, v1
	v_lshl_add_u32 v1, v1, 2, v133
	ds_add_u32 v1, v228
